# prologue S5 table rows: the 40 B/C loads issued at the top of the item with lambda and step (vmcnt(42) for the step), one round trip for the whole item
# speedup vs baseline: 1.0025x; 1.0006x over previous
; __device__ __forceinline__ void prologue(const Args& a, LAS unsigned char* lds, int tid, int wave, int lane) {
;     ...
;         const float lre = a.in[I_LRE][i], lim = a.in[I_LIM][i], step = expf(a.in[I_LSTEP][l * NG + g]);
;         const float mag = expf(lre * step), ar = mag * cosf(lim * step), ai = mag * sinf(lim * step), den = lre * lre + lim * lim;
;         const float cr = ((ar - 1.f) * lre + ai * lim) / den, ci = (ai * lre - (ar - 1.f) * lim) / den;
;         float pr = ar, pi = ai;
; #pragma unroll
;         for (int k = 0; k < 8; ++k) { const float nr = pr * pr - pi * pi, ni = 2.f * pr * pi; pr = nr; pi = ni; }
;         ((f32x4*)(ws + WS_TA))[i] = (f32x4){ar, ai, pr, pi};
;         bf16_t* tbh = (bf16_t*)(ws + WS_TB) + (size_t)(l * NG + g) * 128 * GC;
;         const float* bre = a.in[I_BRE] + (size_t)i * GC; const float* bim = a.in[I_BIM] + (size_t)i * GC;
.LBB0_141:
	s_or_b64 exec, exec, s[0:1]
	s_waitcnt vmcnt(0)
	v_mul_f32_e32 v21, v19, v21
	v_mul_f32_e32 v24, 0x3fb8aa3b, v21
	v_fma_f32 v25, v21, s24, -v24
	v_rndne_f32_e32 v27, v24
	v_fmac_f32_e32 v25, 0x32a5705f, v21
	v_sub_f32_e32 v24, v24, v27
	v_add_f32_e32 v24, v24, v25
	v_cvt_i32_f32_e32 v25, v27
	v_exp_f32_e32 v24, v24
	v_cmp_ngt_f32_e32 vcc, s25, v21
	v_readlane_b32 s36, v252, 16
	v_readlane_b32 s37, v252, 17
	v_ldexp_f32 v24, v24, v25
	v_cndmask_b32_e32 v24, 0, v24, vcc
	v_cmp_nlt_f32_e32 vcc, s26, v21
	v_mul_f32_e32 v21, v23, v23
	v_lshlrev_b64 v[6:7], 12, v[6:7]
	v_cndmask_b32_e32 v34, v11, v24, vcc
	v_fmamk_f32 v24, v21, 0xb94c1982, v12
	v_fmaak_f32 v24, v21, v24, 0xbe2aaa9d
	v_mul_f32_e32 v24, v21, v24
	v_fmac_f32_e32 v23, v23, v24
	v_fmamk_f32 v24, v21, 0x37d75334, v13
	v_fmaak_f32 v24, v21, v24, 0x3d2aabf7
	v_fmaak_f32 v24, v21, v24, 0xbf000004
	v_fma_f32 v21, v21, v24, 1.0
	v_and_b32_e32 v24, 1, v22
	v_cmp_eq_u32_e32 vcc, 0, v24
	v_lshlrev_b32_e32 v22, 30, v22
	v_readlane_b32 s38, v252, 18
	v_cndmask_b32_e64 v21, -v23, v21, vcc
	v_bitop3_b32 v21, v22, v21, s64 bitop3:0x6c
	v_cmp_class_f32_e64 vcc, v5, s52
	v_xor_b32_e32 v5, v20, v5
	v_readlane_b32 s39, v252, 19
	v_cndmask_b32_e32 v35, v16, v21, vcc
	v_mul_f32_e32 v21, v26, v26
	v_fmamk_f32 v23, v21, 0xb94c1982, v12
	v_fmaak_f32 v23, v21, v23, 0xbe2aaa9d
	v_mul_f32_e32 v23, v21, v23
	v_fmac_f32_e32 v26, v26, v23
	v_fmamk_f32 v23, v21, 0x37d75334, v13
	v_fmaak_f32 v23, v21, v23, 0x3d2aabf7
	v_fmaak_f32 v23, v21, v23, 0xbf000004
	v_fma_f32 v21, v21, v23, 1.0
	v_and_b32_e32 v23, 1, v2
	v_lshlrev_b32_e32 v2, 30, v2
	v_cmp_eq_u32_e64 s[0:1], 0, v23
	v_and_b32_e32 v2, 0x80000000, v2
	v_xor_b32_e32 v2, v5, v2
	v_cndmask_b32_e64 v21, v21, v26, s[0:1]
	v_xor_b32_e32 v2, v2, v21
	v_mul_f32_e32 v22, v34, v35
	v_cndmask_b32_e32 v2, v16, v2, vcc
	v_mov_b32_e32 v5, v22
	v_mul_f32_e32 v26, v34, v2
	v_pk_mul_f32 v[20:21], v[22:23], v[4:5] op_sel_hi:[0,1]
	v_mul_f32_e32 v27, v26, v26
	v_pk_mul_f32 v[20:21], v[20:21], v[26:27]
	v_pk_fma_f32 v[24:25], v[22:23], v[4:5], v[26:27] op_sel_hi:[0,1,1] neg_lo:[0,0,1] neg_hi:[0,0,1]
	v_mov_b32_e32 v21, v25
	v_mul_f32_e32 v2, v25, v25
	v_pk_fma_f32 v[28:29], v[20:21], v[20:21], v[2:3] op_sel_hi:[1,1,0] neg_lo:[1,0,0] neg_hi:[1,0,0]
	v_add_f32_e32 v2, v25, v25
	v_mul_f32_e32 v29, v20, v2
	v_mul_f32_e32 v2, v29, v29
	v_pk_fma_f32 v[24:25], v[28:29], v[28:29], v[2:3] op_sel_hi:[1,1,0] neg_lo:[0,0,1] neg_hi:[0,0,1]
	v_add_f32_e32 v21, v28, v28
	v_mov_b32_e32 v28, v24
	v_mov_b32_e32 v20, v24
	v_pk_mul_f32 v[20:21], v[28:29], v[20:21]
	v_mov_b32_e32 v29, v4
	v_pk_mov_b32 v[24:25], v[20:21], v[24:25] op_sel:[1,0]
	v_mov_b32_e32 v28, v21
	v_pk_mul_f32 v[30:31], v[24:25], v[28:29]
	v_pk_fma_f32 v[24:25], v[24:25], v[28:29], v[20:21] neg_lo:[1,0,0] neg_hi:[1,0,0]
	v_pk_mul_f32 v[28:29], v[20:21], v[30:31]
	v_pk_mov_b32 v[20:21], v[20:21], v[24:25] op_sel:[1,0]
	v_mov_b32_e32 v30, v31
	v_mov_b32_e32 v31, v4
	v_pk_mul_f32 v[20:21], v[20:21], v[30:31]
	v_mov_b32_e32 v32, v24
	v_mov_b32_e32 v33, v29
	v_mov_b32_e32 v25, v21
	v_pk_mul_f32 v[24:25], v[32:33], v[24:25]
	v_pk_mul_f32 v[30:31], v[28:29], v[20:21]
	v_pk_fma_f32 v[20:21], v[28:29], v[20:21], v[24:25] op_sel:[1,0,0] neg_lo:[1,0,0] neg_hi:[1,0,0]
	v_pk_mul_f32 v[28:29], v[24:25], v[30:31]
	v_mov_b32_e32 v30, v20
	v_mov_b32_e32 v31, v4
	v_pk_mul_f32 v[32:33], v[20:21], v[30:31] op_sel_hi:[0,1]
	v_mov_b32_e32 v24, v29
	v_pk_fma_f32 v[20:21], v[20:21], v[30:31], v[24:25] op_sel_hi:[0,1,1] neg_lo:[0,0,1] neg_hi:[0,0,1]
	v_pk_mul_f32 v[24:25], v[32:33], v[24:25]
	v_add_f32_e32 v29, v20, v20
	v_mov_b32_e32 v21, v25
	v_mul_f32_e32 v2, v25, v25
	v_pk_fma_f32 v[20:21], v[20:21], v[20:21], v[2:3] op_sel_hi:[1,1,0] neg_lo:[0,0,1] neg_hi:[0,0,1]
	v_mov_b32_e32 v23, v26
	v_mov_b32_e32 v24, v20
	v_mov_b32_e32 v28, v20
	v_pk_mul_f32 v[28:29], v[24:25], v[28:29]
	v_mov_b32_e32 v25, v4
	v_pk_mov_b32 v[20:21], v[28:29], v[20:21] op_sel:[1,0]
	v_mov_b32_e32 v24, v29
	v_pk_add_f32 v[30:31], v[20:21], v[20:21]
	v_pk_fma_f32 v[24:25], v[20:21], v[24:25], v[28:29] neg_lo:[1,0,0] neg_hi:[1,0,0]
	v_pk_mul_f32 v[20:21], v[28:29], v[30:31]
	v_lshl_add_u64 v[28:29], v[0:1], 4, s[10:11]
	v_mov_b32_e32 v25, v21
	v_lshlrev_b64 v[20:21], 6, v[0:1]
	global_store_dwordx4 v[28:29], v[22:25], off
	v_mul_f32_e32 v1, v18, v18
	v_fma_f32 v2, v34, v35, -1.0
	v_lshl_add_u64 v[22:23], s[86:87], 0, v[20:21]
	v_lshl_add_u64 v[20:21], s[36:37], 0, v[20:21]
	v_mov_b64_e32 v[24:25], v[104:105]
	v_mov_b64_e32 v[28:29], v[120:121]
	v_mul_f32_e32 v5, v18, v26
	v_fmac_f32_e32 v5, v19, v2
	v_fmac_f32_e32 v1, v19, v19
	v_div_scale_f32 v27, s[0:1], v1, v1, v5
	v_rcp_f32_e32 v30, v27
	v_mul_f32_e32 v2, v18, v2
	v_fma_f32 v2, v19, v26, -v2
	v_readlane_b32 s40, v252, 20
	v_fma_f32 v18, -v27, v30, 1.0
	v_fmac_f32_e32 v30, v18, v30
	v_div_scale_f32 v18, vcc, v5, v1, v5
	v_mul_f32_e32 v19, v18, v30
	v_fma_f32 v26, -v27, v19, v18
	v_fmac_f32_e32 v19, v26, v30
	v_div_scale_f32 v26, s[0:1], v1, v1, v2
	v_fma_f32 v18, -v27, v19, v18
	v_rcp_f32_e32 v27, v26
	v_div_fmas_f32 v18, v18, v30, v19
	v_div_fixup_f32 v5, v18, v1, v5
	v_readlane_b32 s41, v252, 21
	v_fma_f32 v18, -v26, v27, 1.0
	v_fmac_f32_e32 v27, v18, v27
	v_div_scale_f32 v18, vcc, v2, v1, v2
	v_mul_f32_e32 v19, v18, v27
	v_fma_f32 v30, -v26, v19, v18
	v_fmac_f32_e32 v19, v30, v27
	v_fma_f32 v18, -v26, v19, v18
	v_div_fmas_f32 v18, v18, v27, v19
	v_div_fixup_f32 v1, v18, v1, v2
	v_lshlrev_b32_e32 v2, 11, v17
	v_sub_u32_e32 v26, v9, v2
	v_lshl_add_u64 v[18:19], s[12:13], 0, v[6:7]
	v_ashrrev_i32_e32 v27, 31, v26
	v_lshl_add_u64 v[18:19], v[26:27], 1, v[18:19]
	v_add_u32_e32 v9, s22, v9
	v_readlane_b32 s42, v252, 22
; __device__ __forceinline__ unsigned pk2(float lo, float hi) { return pg8::cvt_pk_bf16(lo, hi); }
; __device__ __forceinline__ void prologue(const Args& a, LAS unsigned char* lds, int tid, int wave, int lane) {
;     ...
;         const float cr = ((ar - 1.f) * lre + ai * lim) / den, ci = (ai * lre - (ar - 1.f) * lim) / den;
;         float pr = ar, pi = ai;
; #pragma unroll
;         for (int k = 0; k < 8; ++k) { const float nr = pr * pr - pi * pi, ni = 2.f * pr * pi; pr = nr; pi = ni; }
;         ((f32x4*)(ws + WS_TA))[i] = (f32x4){ar, ai, pr, pi};
;         bf16_t* tbh = (bf16_t*)(ws + WS_TB) + (size_t)(l * NG + g) * 128 * GC;
;         const float* bre = a.in[I_BRE] + (size_t)i * GC; const float* bim = a.in[I_BIM] + (size_t)i * GC;
; #pragma unroll
;         for (int c = 0; c < GC; c += 2) { const float br0 = bre[c], bi0 = bim[c], br1 = bre[c + 1], bi1 = bim[c + 1];
;             *(unsigned*)(tbh + (2 * p) * GC + c) = pk2(cr * br0 - ci * bi0, cr * br1 - ci * bi1); *(unsigned*)(tbh + (2 * p + 1) * GC + c) = pk2(cr * bi0 + ci * br0, cr * bi1 + ci * br1); }
	v_readlane_b32 s43, v252, 23
	v_readlane_b32 s44, v252, 24
	v_readlane_b32 s45, v252, 25
	v_readlane_b32 s46, v252, 26
	v_readlane_b32 s47, v252, 27
	v_readlane_b32 s48, v252, 28
	v_readlane_b32 s49, v252, 29
	v_readlane_b32 s50, v252, 30
	v_readlane_b32 s51, v252, 31
	s_nop 0
	v_mul_f32_e32 v2, v24, v1
	s_nop 0
	v_fma_f32 v2, v28, v5, -v2
	v_mul_f32_e32 v26, v25, v1
	v_fma_f32 v26, v29, v5, -v26
	v_cvt_pk_bf16_f32 v2, v2, v26
	global_store_dword v[18:19], v2, off
	v_mul_f32_e32 v2, v24, v5
	v_mul_f32_e32 v24, v25, v5
	v_fmac_f32_e32 v2, v28, v1
	v_fmac_f32_e32 v24, v29, v1
	v_cvt_pk_bf16_f32 v2, v2, v24
	v_mov_b64_e32 v[24:25], v[106:107]
	v_mov_b64_e32 v[26:27], v[122:123]
	s_nop 0
	v_mul_f32_e32 v28, v1, v25
	global_store_dword v[18:19], v2, off offset:32
	v_mul_f32_e32 v2, v24, v1
	v_mul_f32_e32 v24, v24, v5
	v_mul_f32_e32 v25, v5, v25
	s_nop 0
	v_fma_f32 v2, v26, v5, -v2
	v_fma_f32 v28, v27, v5, -v28
	v_fmac_f32_e32 v24, v26, v1
	v_fmac_f32_e32 v25, v27, v1
	v_cvt_pk_bf16_f32 v2, v2, v28
	global_store_dword v[18:19], v2, off offset:4
	v_cvt_pk_bf16_f32 v2, v24, v25
	v_mov_b64_e32 v[24:25], v[108:109]
	v_mov_b64_e32 v[26:27], v[124:125]
	s_nop 0
	v_mul_f32_e32 v28, v1, v25
	global_store_dword v[18:19], v2, off offset:36
	v_mul_f32_e32 v2, v1, v24
	v_mul_f32_e32 v24, v5, v24
	v_mul_f32_e32 v25, v5, v25
	s_nop 0
	v_fma_f32 v2, v5, v26, -v2
	v_fma_f32 v28, v5, v27, -v28
	v_fmac_f32_e32 v24, v1, v26
	v_fmac_f32_e32 v25, v1, v27
	v_cvt_pk_bf16_f32 v2, v2, v28
	global_store_dword v[18:19], v2, off offset:8
	v_cvt_pk_bf16_f32 v2, v24, v25
	v_mov_b64_e32 v[24:25], v[110:111]
	v_mov_b64_e32 v[26:27], v[126:127]
	s_nop 0
	v_mul_f32_e32 v28, v1, v25
	global_store_dword v[18:19], v2, off offset:40
	v_mul_f32_e32 v2, v1, v24
	v_mul_f32_e32 v24, v5, v24
	v_mul_f32_e32 v25, v5, v25
	s_nop 0
	v_fma_f32 v2, v5, v26, -v2
	v_fma_f32 v28, v5, v27, -v28
	v_fmac_f32_e32 v24, v1, v26
	v_fmac_f32_e32 v25, v1, v27
	v_cvt_pk_bf16_f32 v2, v2, v28
	global_store_dword v[18:19], v2, off offset:12
	v_cvt_pk_bf16_f32 v2, v24, v25
	v_mov_b64_e32 v[24:25], v[112:113]
	v_mov_b64_e32 v[26:27], v[128:129]
	s_nop 0
	v_mul_f32_e32 v28, v1, v25
	global_store_dword v[18:19], v2, off offset:44
	v_mul_f32_e32 v2, v1, v24
	v_mul_f32_e32 v24, v5, v24
	v_mul_f32_e32 v25, v5, v25
	s_nop 0
	v_fma_f32 v2, v5, v26, -v2
	v_fma_f32 v28, v5, v27, -v28
	v_fmac_f32_e32 v24, v1, v26
	v_fmac_f32_e32 v25, v1, v27
	v_cvt_pk_bf16_f32 v2, v2, v28
	global_store_dword v[18:19], v2, off offset:16
	v_cvt_pk_bf16_f32 v2, v24, v25
	v_mov_b64_e32 v[24:25], v[114:115]
	v_mov_b64_e32 v[26:27], v[130:131]
	s_nop 0
	v_mul_f32_e32 v28, v1, v25
	global_store_dword v[18:19], v2, off offset:48
	v_mul_f32_e32 v2, v1, v24
	v_mul_f32_e32 v24, v5, v24
	v_mul_f32_e32 v25, v5, v25
	s_nop 0
	v_fma_f32 v2, v5, v26, -v2
	v_fma_f32 v28, v5, v27, -v28
	v_fmac_f32_e32 v24, v1, v26
	v_fmac_f32_e32 v25, v1, v27
	v_cvt_pk_bf16_f32 v2, v2, v28
	global_store_dword v[18:19], v2, off offset:20
	v_cvt_pk_bf16_f32 v2, v24, v25
	v_mov_b64_e32 v[24:25], v[116:117]
	v_mov_b64_e32 v[26:27], v[132:133]
	s_nop 0
	v_mul_f32_e32 v28, v1, v25
	global_store_dword v[18:19], v2, off offset:52
	v_mul_f32_e32 v2, v1, v24
	s_nop 0
	v_fma_f32 v2, v5, v26, -v2
	v_mul_f32_e32 v24, v5, v24
	v_mul_f32_e32 v25, v5, v25
	v_fma_f32 v28, v5, v27, -v28
	v_cvt_pk_bf16_f32 v2, v2, v28
	v_fmac_f32_e32 v24, v1, v26
	v_fmac_f32_e32 v25, v1, v27
	global_store_dword v[18:19], v2, off offset:24
	v_cvt_pk_bf16_f32 v2, v24, v25
	v_mov_b64_e32 v[20:21], v[118:119]
	s_nop 0
	v_mov_b64_e32 v[22:23], v[134:135]
	v_lshlrev_b32_e32 v24, 6, v17
	v_sub_u32_e32 v24, v0, v24
	v_ashrrev_i32_e32 v25, 31, v24
	v_lshl_add_u64 v[26:27], s[38:39], 0, v[6:7]
	v_lshl_add_u64 v[28:29], s[40:41], 0, v[6:7]
	v_lshlrev_b64 v[30:31], 2, v[24:25]
	global_store_dword v[18:19], v2, off offset:56
	v_lshl_add_u64 v[32:33], v[26:27], 0, v[30:31]
	v_lshl_add_u64 v[30:31], v[28:29], 0, v[30:31]
	v_lshl_add_u64 v[6:7], s[14:15], 0, v[6:7]
	v_add_u32_e32 v0, s3, v0
	v_cmp_lt_i32_e32 vcc, s53, v0
	s_or_b64 s[16:17], vcc, s[16:17]
	s_nop 0
	v_mul_f32_e32 v2, v1, v20
	v_mul_f32_e32 v25, v1, v21
	v_mul_f32_e32 v20, v5, v20
	v_mul_f32_e32 v21, v5, v21
	s_nop 0
	v_fma_f32 v2, v5, v22, -v2
	v_fma_f32 v5, v5, v23, -v25
	v_fmac_f32_e32 v20, v1, v22
	v_fmac_f32_e32 v21, v1, v23
	v_cvt_pk_bf16_f32 v1, v2, v5
	global_store_dword v[18:19], v1, off offset:28
	v_cvt_pk_bf16_f32 v1, v20, v21
	v_mov_b32_e32 v5, v64
	v_mov_b32_e32 v25, v142
	v_add_u32_e32 v2, 64, v24
	v_lshlrev_b64 v[20:21], 2, v[2:3]
	v_lshl_add_u64 v[22:23], v[26:27], 0, v[20:21]
	v_lshl_add_u64 v[20:21], v[28:29], 0, v[20:21]
	global_store_dword v[18:19], v1, off offset:60
	v_lshlrev_b32_e32 v2, 7, v17
	v_sub_u32_e32 v18, v10, v2
	v_ashrrev_i32_e32 v19, 31, v18
	v_add_u32_e32 v2, 0x80, v24
	v_lshl_add_u64 v[6:7], v[18:19], 1, v[6:7]
	v_lshlrev_b64 v[18:19], 2, v[2:3]
	v_add_u32_e32 v2, 0xc0, v24
	v_add_u32_e32 v10, s23, v10
	s_nop 0
	v_xor_b32_e32 v1, 0x80000000, v5
	s_nop 0
	v_cvt_pk_bf16_f32 v1, v25, v1
	v_mov_b32_e32 v5, v65
	s_nop 0
	v_mov_b32_e32 v22, v143
	v_lshl_add_u64 v[20:21], v[26:27], 0, v[18:19]
	v_lshl_add_u64 v[18:19], v[28:29], 0, v[18:19]
	global_store_dword v[6:7], v1, off
	s_nop 0
	v_xor_b32_e32 v1, 0x80000000, v5
	s_nop 0
	v_cvt_pk_bf16_f32 v1, v22, v1
	v_mov_b32_e32 v5, v66
	v_mov_b32_e32 v17, v144
	v_lshlrev_b64 v[18:19], 2, v[2:3]
	v_lshl_add_u64 v[20:21], v[26:27], 0, v[18:19]
	v_lshl_add_u64 v[18:19], v[28:29], 0, v[18:19]
	global_store_dword v[6:7], v1, off offset:256
	v_add_u32_e32 v2, 0x100, v24
	s_nop 0
	v_xor_b32_e32 v1, 0x80000000, v5
	s_nop 0
	v_cvt_pk_bf16_f32 v1, v17, v1
	v_mov_b32_e32 v5, v67
; __device__ __forceinline__ unsigned pk2(float lo, float hi) { return pg8::cvt_pk_bf16(lo, hi); }
; __device__ __forceinline__ void prologue(const Args& a, LAS unsigned char* lds, int tid, int wave, int lane) {
;     ...
;         bf16_t* tc = (bf16_t*)(ws + WS_TC) + (size_t)(l * NG + g) * GC * 128;
;         const float* cre = a.in[I_CRE] + (size_t)(l * NG + g) * GC * NP; const float* cim = a.in[I_CIM] + (size_t)(l * NG + g) * GC * NP;
; #pragma unroll
;         for (int c = 0; c < GC; ++c) *(unsigned*)(tc + c * 128 + 2 * p) = pk2(cre[c * NP + p], -cim[c * NP + p]);
	v_mov_b32_e32 v17, v145
	v_lshlrev_b64 v[18:19], 2, v[2:3]
	v_lshl_add_u64 v[20:21], v[26:27], 0, v[18:19]
	v_lshl_add_u64 v[18:19], v[28:29], 0, v[18:19]
	global_store_dword v[6:7], v1, off offset:512
	v_add_u32_e32 v2, 0x140, v24
	s_nop 0
	v_xor_b32_e32 v1, 0x80000000, v5
	s_nop 0
	v_cvt_pk_bf16_f32 v1, v17, v1
	v_mov_b32_e32 v5, v68
	v_mov_b32_e32 v17, v146
	v_lshlrev_b64 v[18:19], 2, v[2:3]
	v_lshl_add_u64 v[20:21], v[26:27], 0, v[18:19]
	v_lshl_add_u64 v[18:19], v[28:29], 0, v[18:19]
	global_store_dword v[6:7], v1, off offset:768
	v_add_u32_e32 v2, 0x180, v24
	s_nop 0
	v_xor_b32_e32 v1, 0x80000000, v5
	s_nop 0
	v_cvt_pk_bf16_f32 v1, v17, v1
	v_mov_b32_e32 v5, v69
	v_mov_b32_e32 v17, v147
	v_lshlrev_b64 v[18:19], 2, v[2:3]
	v_lshl_add_u64 v[20:21], v[26:27], 0, v[18:19]
	v_lshl_add_u64 v[18:19], v[28:29], 0, v[18:19]
	global_store_dword v[6:7], v1, off offset:1024
	v_add_u32_e32 v2, 0x1c0, v24
	s_nop 0
	v_xor_b32_e32 v1, 0x80000000, v5
	s_nop 0
	v_cvt_pk_bf16_f32 v1, v17, v1
	v_mov_b32_e32 v5, v70
	v_mov_b32_e32 v17, v148
	v_lshlrev_b64 v[18:19], 2, v[2:3]
	v_lshl_add_u64 v[20:21], v[26:27], 0, v[18:19]
	v_lshl_add_u64 v[18:19], v[28:29], 0, v[18:19]
	global_store_dword v[6:7], v1, off offset:1280
	v_add_u32_e32 v2, 0x200, v24
	s_nop 0
	v_xor_b32_e32 v1, 0x80000000, v5
	s_nop 0
	v_cvt_pk_bf16_f32 v1, v17, v1
	v_mov_b32_e32 v5, v71
	v_mov_b32_e32 v17, v149
	v_lshlrev_b64 v[18:19], 2, v[2:3]
	v_lshl_add_u64 v[20:21], v[26:27], 0, v[18:19]
	v_lshl_add_u64 v[18:19], v[28:29], 0, v[18:19]
	global_store_dword v[6:7], v1, off offset:1536
	v_add_u32_e32 v2, 0x240, v24
	s_nop 0
	v_xor_b32_e32 v1, 0x80000000, v5
	s_nop 0
	v_cvt_pk_bf16_f32 v1, v17, v1
	v_mov_b32_e32 v5, v72
	v_mov_b32_e32 v17, v150
	v_lshlrev_b64 v[18:19], 2, v[2:3]
	v_lshl_add_u64 v[20:21], v[26:27], 0, v[18:19]
	v_lshl_add_u64 v[18:19], v[28:29], 0, v[18:19]
	global_store_dword v[6:7], v1, off offset:1792
	v_add_u32_e32 v2, 0x280, v24
	s_nop 0
	v_xor_b32_e32 v1, 0x80000000, v5
	s_nop 0
	v_cvt_pk_bf16_f32 v1, v17, v1
	v_mov_b32_e32 v5, v73
	v_mov_b32_e32 v17, v151
	v_lshlrev_b64 v[18:19], 2, v[2:3]
	v_lshl_add_u64 v[20:21], v[26:27], 0, v[18:19]
	v_lshl_add_u64 v[18:19], v[28:29], 0, v[18:19]
	global_store_dword v[6:7], v1, off offset:2048
	v_add_u32_e32 v2, 0x2c0, v24
	s_nop 0
	v_xor_b32_e32 v1, 0x80000000, v5
	s_nop 0
	v_cvt_pk_bf16_f32 v1, v17, v1
	v_mov_b32_e32 v5, v74
	v_mov_b32_e32 v17, v152
	v_lshlrev_b64 v[18:19], 2, v[2:3]
	v_lshl_add_u64 v[20:21], v[26:27], 0, v[18:19]
	v_lshl_add_u64 v[18:19], v[28:29], 0, v[18:19]
	global_store_dword v[6:7], v1, off offset:2304
	v_add_u32_e32 v2, 0x300, v24
	s_nop 0
	v_xor_b32_e32 v1, 0x80000000, v5
	s_nop 0
	v_cvt_pk_bf16_f32 v1, v17, v1
	v_mov_b32_e32 v5, v75
	v_mov_b32_e32 v17, v153
	v_lshlrev_b64 v[18:19], 2, v[2:3]
	v_lshl_add_u64 v[20:21], v[26:27], 0, v[18:19]
	v_lshl_add_u64 v[18:19], v[28:29], 0, v[18:19]
	global_store_dword v[6:7], v1, off offset:2560
	v_add_u32_e32 v2, 0x340, v24
	s_nop 0
	v_xor_b32_e32 v1, 0x80000000, v5
	s_nop 0
	v_cvt_pk_bf16_f32 v1, v17, v1
	v_mov_b32_e32 v5, v76
	v_mov_b32_e32 v17, v154
	v_lshlrev_b64 v[18:19], 2, v[2:3]
	v_lshl_add_u64 v[20:21], v[26:27], 0, v[18:19]
	v_lshl_add_u64 v[18:19], v[28:29], 0, v[18:19]
	global_store_dword v[6:7], v1, off offset:2816
	v_add_u32_e32 v2, 0x380, v24
	s_nop 0
	v_xor_b32_e32 v1, 0x80000000, v5
	s_nop 0
	v_cvt_pk_bf16_f32 v1, v17, v1
	v_mov_b32_e32 v5, v77
	v_mov_b32_e32 v17, v155
	v_lshlrev_b64 v[18:19], 2, v[2:3]
	v_lshl_add_u64 v[20:21], v[26:27], 0, v[18:19]
	v_lshl_add_u64 v[18:19], v[28:29], 0, v[18:19]
	global_store_dword v[6:7], v1, off offset:3072
	v_add_u32_e32 v2, 0x3c0, v24
	s_nop 0
	v_xor_b32_e32 v1, 0x80000000, v5
	s_nop 0
	v_cvt_pk_bf16_f32 v1, v17, v1
	v_mov_b32_e32 v5, v78
	v_mov_b32_e32 v17, v156
	v_lshlrev_b64 v[18:19], 2, v[2:3]
	v_lshl_add_u64 v[20:21], v[26:27], 0, v[18:19]
	v_lshl_add_u64 v[18:19], v[28:29], 0, v[18:19]
	global_store_dword v[6:7], v1, off offset:3328
	s_nop 0
	v_xor_b32_e32 v1, 0x80000000, v5
	s_nop 0
	v_cvt_pk_bf16_f32 v1, v17, v1
	v_mov_b32_e32 v2, v79
	v_mov_b32_e32 v5, v157
	s_nop 0
	global_store_dword v[6:7], v1, off offset:3584
	s_nop 0
	v_xor_b32_e32 v1, 0x80000000, v2
	s_nop 0
	v_cvt_pk_bf16_f32 v1, v5, v1
	global_store_dword v[6:7], v1, off offset:3840
	s_andn2_b64 exec, exec, s[16:17]
	s_cbranch_execz .LBB0_150
; __device__ __forceinline__ unsigned pk2(float lo, float hi) { return pg8::cvt_pk_bf16(lo, hi); }
; __device__ __forceinline__ void prologue(const Args& a, LAS unsigned char* lds, int tid, int wave, int lane) {
;     ...
;     for (int i = tid < 16 ? (int)blockIdx.x * 16 + tid : 2 * NG * NP; i < 2 * NG * NP; i += gridDim.x * 16) {
;         const int l = i / (NG * NP), g = (i / NP) % NG, p = i % NP;
;         const float lre = a.in[I_LRE][i], lim = a.in[I_LIM][i], step = expf(a.in[I_LSTEP][l * NG + g]);
;         const float mag = expf(lre * step), ar = mag * cosf(lim * step), ai = mag * sinf(lim * step), den = lre * lre + lim * lim;
;     ...
;         const float* bre = a.in[I_BRE] + (size_t)i * GC; const float* bim = a.in[I_BIM] + (size_t)i * GC;
; #pragma unroll
;         for (int c = 0; c < GC; c += 2) { const float br0 = bre[c], bi0 = bim[c], br1 = bre[c + 1], bi1 = bim[c + 1];
;             *(unsigned*)(tbh + (2 * p) * GC + c) = pk2(cr * br0 - ci * bi0, cr * br1 - ci * bi1); *(unsigned*)(tbh + (2 * p + 1) * GC + c) = pk2(cr * bi0 + ci * br0, cr * bi1 + ci * br1); }
;         bf16_t* tc = (bf16_t*)(ws + WS_TC) + (size_t)(l * NG + g) * GC * 128;
;         const float* cre = a.in[I_CRE] + (size_t)(l * NG + g) * GC * NP; const float* cim = a.in[I_CIM] + (size_t)(l * NG + g) * GC * NP;
; #pragma unroll
;         for (int c = 0; c < GC; ++c) *(unsigned*)(tc + c * 128 + 2 * p) = pk2(cre[c * NP + p], -cim[c * NP + p]);
.LBB0_142:
	v_ashrrev_i32_e32 v1, 31, v0
	v_lshrrev_b32_e32 v5, 26, v1
	v_add_u32_e32 v5, v0, v5
	v_ashrrev_i32_e32 v17, 6, v5
	v_lshrrev_b32_e32 v5, 27, v17
	v_lshrrev_b32_e32 v2, 21, v1
	v_add_u32_e32 v5, v17, v5
	v_add_u32_e32 v2, v0, v2
	v_and_b32_e32 v5, 0xffffffe0, v5
	v_ashrrev_i32_e32 v2, 11, v2
	v_sub_u32_e32 v5, v17, v5
	v_lshl_add_u32 v6, v2, 5, v5
	v_ashrrev_i32_e32 v7, 31, v6
	v_lshl_add_u64 v[18:19], v[6:7], 2, s[84:85]
	global_load_dword v2, v[18:19], off
	s_waitcnt vmcnt(3)
	v_lshlrev_b64 v[20:21], 2, v[0:1]
	v_lshl_add_u64 v[18:19], s[82:83], 0, v[20:21]
	global_load_dword v18, v[18:19], off
	v_lshl_add_u64 v[20:21], s[80:81], 0, v[20:21]
	global_load_dword v19, v[20:21], off
	v_readlane_b32 s98, v252, 16
	v_readlane_b32 s99, v252, 17
	v_readlane_b32 s100, v252, 20
	v_readlane_b32 s101, v252, 21
	v_lshlrev_b32_e32 v136, 6, v0
	v_mov_b32_e32 v137, 0
	v_lshl_add_u64 v[138:139], s[98:99], 0, v[136:137]
	v_lshl_add_u64 v[140:141], s[86:87], 0, v[136:137]
	v_readlane_b32 s98, v252, 18
	v_readlane_b32 s99, v252, 19
	global_load_dwordx4 v[104:107], v[138:139], off
	global_load_dwordx4 v[108:111], v[138:139], off offset:16
	global_load_dwordx4 v[112:115], v[138:139], off offset:32
	global_load_dwordx4 v[116:119], v[138:139], off offset:48
	global_load_dwordx4 v[120:123], v[140:141], off
	global_load_dwordx4 v[124:127], v[140:141], off offset:16
	global_load_dwordx4 v[128:131], v[140:141], off offset:32
	global_load_dwordx4 v[132:135], v[140:141], off offset:48
	v_lshlrev_b32_e32 v136, 12, v17
	v_and_b32_e32 v138, 63, v0
	v_lshl_add_u32 v136, v138, 2, v136
	v_lshl_add_u64 v[138:139], s[98:99], 0, v[136:137]
	v_lshl_add_u64 v[140:141], s[100:101], 0, v[136:137]
	global_load_dword v64, v[140:141], off
	global_load_dword v142, v[138:139], off
	global_load_dword v65, v[140:141], off offset:256
	global_load_dword v143, v[138:139], off offset:256
	global_load_dword v66, v[140:141], off offset:512
	global_load_dword v144, v[138:139], off offset:512
	global_load_dword v67, v[140:141], off offset:768
	global_load_dword v145, v[138:139], off offset:768
	global_load_dword v68, v[140:141], off offset:1024
	global_load_dword v146, v[138:139], off offset:1024
	global_load_dword v69, v[140:141], off offset:1280
	global_load_dword v147, v[138:139], off offset:1280
	global_load_dword v70, v[140:141], off offset:1536
	global_load_dword v148, v[138:139], off offset:1536
	global_load_dword v71, v[140:141], off offset:1792
	global_load_dword v149, v[138:139], off offset:1792
	global_load_dword v72, v[140:141], off offset:2048
	global_load_dword v150, v[138:139], off offset:2048
	global_load_dword v73, v[140:141], off offset:2304
	global_load_dword v151, v[138:139], off offset:2304
	global_load_dword v74, v[140:141], off offset:2560
	global_load_dword v152, v[138:139], off offset:2560
	global_load_dword v75, v[140:141], off offset:2816
	global_load_dword v153, v[138:139], off offset:2816
	global_load_dword v76, v[140:141], off offset:3072
	global_load_dword v154, v[138:139], off offset:3072
	global_load_dword v77, v[140:141], off offset:3328
	global_load_dword v155, v[138:139], off offset:3328
	global_load_dword v78, v[140:141], off offset:3584
	global_load_dword v156, v[138:139], off offset:3584
	global_load_dword v79, v[140:141], off offset:3840
	global_load_dword v157, v[138:139], off offset:3840
	s_waitcnt vmcnt(42)
	v_mul_f32_e32 v5, 0x3fb8aa3b, v2
	v_fma_f32 v20, v2, s24, -v5
	v_rndne_f32_e32 v21, v5
	v_fmac_f32_e32 v20, 0x32a5705f, v2
	v_sub_f32_e32 v5, v5, v21
	v_add_f32_e32 v5, v5, v20
	v_cvt_i32_f32_e32 v21, v21
	v_exp_f32_e32 v5, v5
	v_cmp_ngt_f32_e32 vcc, s25, v2
	v_ldexp_f32 v5, v5, v21
	s_nop 0
	v_cndmask_b32_e32 v5, 0, v5, vcc
	v_cmp_nlt_f32_e32 vcc, s26, v2
	s_nop 1
	v_cndmask_b32_e32 v21, v11, v5, vcc
	s_waitcnt vmcnt(1)
	v_mul_f32_e32 v5, v18, v21
	v_and_b32_e32 v20, 0x7fffffff, v5
	v_lshrrev_b32_e32 v2, 23, v20
	v_and_b32_e32 v22, 0x7fffff, v20
	v_cmp_nlt_f32_e64 s[18:19], |v5|, s27
	v_add_u32_e32 v25, 0xffffff88, v2
	v_or_b32_e32 v24, 0x800000, v22
	s_and_saveexec_b64 s[0:1], s[18:19]
	s_xor_b64 s[20:21], exec, s[0:1]
	s_cbranch_execz .LBB0_144
	v_cmp_lt_u32_e32 vcc, 63, v25
	s_nop 1
	v_cndmask_b32_e32 v2, 0, v14, vcc
	v_add_u32_e32 v2, v2, v25
	v_cmp_lt_u32_e64 s[0:1], 31, v2
	s_nop 1
	v_cndmask_b32_e64 v22, 0, v15, s[0:1]
	v_add_u32_e32 v2, v22, v2
	v_cmp_lt_u32_e64 s[4:5], 31, v2
	s_nop 1
	v_cndmask_b32_e64 v22, 0, v15, s[4:5]
	v_add_u32_e32 v38, v22, v2
	v_mad_u64_u32 v[22:23], s[6:7], v24, s28, 0
	v_mov_b32_e32 v2, v23
	v_mad_u64_u32 v[26:27], s[6:7], v24, s29, v[2:3]
	v_mov_b32_e32 v2, v27
	v_mad_u64_u32 v[28:29], s[6:7], v24, s33, v[2:3]
	v_mov_b32_e32 v2, v29
	v_mad_u64_u32 v[30:31], s[6:7], v24, s54, v[2:3]
	v_mov_b32_e32 v2, v31
	v_mad_u64_u32 v[32:33], s[6:7], v24, s55, v[2:3]
	v_mov_b32_e32 v2, v33
	v_mad_u64_u32 v[34:35], s[6:7], v24, s56, v[2:3]
	v_mov_b32_e32 v2, v35
	v_mad_u64_u32 v[36:37], s[6:7], v24, s57, v[2:3]
	v_cndmask_b32_e32 v23, v34, v30, vcc
	v_cndmask_b32_e32 v2, v36, v32, vcc
	v_cndmask_b32_e32 v29, v37, v34, vcc
	v_cndmask_b32_e64 v27, v2, v23, s[0:1]
	v_cndmask_b32_e64 v2, v29, v2, s[0:1]
	v_cndmask_b32_e32 v29, v32, v28, vcc
	v_cndmask_b32_e64 v23, v23, v29, s[0:1]
	v_cndmask_b32_e32 v26, v30, v26, vcc
	v_cndmask_b32_e64 v2, v2, v27, s[4:5]
	v_cndmask_b32_e64 v27, v27, v23, s[4:5]
	v_sub_u32_e32 v31, 32, v38
	v_cndmask_b32_e64 v29, v29, v26, s[0:1]
	v_alignbit_b32 v32, v2, v27, v31
	v_cmp_eq_u32_e64 s[6:7], 0, v38
	v_cndmask_b32_e64 v23, v23, v29, s[4:5]
	v_cndmask_b32_e32 v22, v28, v22, vcc
	v_cndmask_b32_e64 v2, v32, v2, s[6:7]
	v_alignbit_b32 v30, v27, v23, v31
	v_cndmask_b32_e64 v22, v26, v22, s[0:1]
	v_cndmask_b32_e64 v27, v30, v27, s[6:7]
	v_bfe_u32 v33, v2, 29, 1
	v_cndmask_b32_e64 v22, v29, v22, s[4:5]
	v_alignbit_b32 v30, v2, v27, 30
	v_sub_u32_e32 v34, 0, v33
	v_alignbit_b32 v26, v23, v22, v31
	v_xor_b32_e32 v30, v30, v34
	v_cndmask_b32_e64 v23, v26, v23, s[6:7]
	v_alignbit_b32 v26, v27, v23, 30
	v_ffbh_u32_e32 v27, v30
	v_min_u32_e32 v27, 32, v27
	v_alignbit_b32 v22, v23, v22, 30
	v_xor_b32_e32 v26, v26, v34
	v_sub_u32_e32 v28, 31, v27
	v_xor_b32_e32 v22, v22, v34
	v_alignbit_b32 v29, v30, v26, v28
	v_alignbit_b32 v22, v26, v22, v28
	v_alignbit_b32 v23, v29, v22, 9
	v_ffbh_u32_e32 v26, v23
	v_min_u32_e32 v26, 32, v26
	v_lshrrev_b32_e32 v32, 29, v2
	v_not_b32_e32 v28, v26
	v_alignbit_b32 v22, v23, v22, v28
	v_lshlrev_b32_e32 v23, 31, v32
	v_or_b32_e32 v28, 0x33000000, v23
	v_add_lshl_u32 v26, v26, v27, 23
	v_lshrrev_b32_e32 v22, 9, v22
	v_sub_u32_e32 v26, v28, v26
	v_or_b32_e32 v23, 0.5, v23
	v_lshlrev_b32_e32 v27, 23, v27
	v_or_b32_e32 v22, v26, v22
	v_lshrrev_b32_e32 v26, 9, v29
	v_sub_u32_e32 v23, v23, v27
	v_or_b32_e32 v23, v26, v23
	v_mul_f32_e32 v26, 0x3fc90fda, v23
	v_fma_f32 v27, v23, s60, -v26
	v_fmac_f32_e32 v27, 0x33a22168, v23
	v_fmac_f32_e32 v27, 0x3fc90fda, v22
	v_lshrrev_b32_e32 v2, 30, v2
	v_add_f32_e32 v23, v26, v27
	v_add_u32_e32 v22, v33, v2
